# diff-attention loop: persistent K fragment address registers (one XOR per trip), A-half V^T addresses reused by B half via +16K immediate offset, 32-bit DMA offset steps
# speedup vs baseline: 1.0088x; 1.0002x over previous
; __device__ __forceinline__ void dattn_unit(LAS unsigned char* lds, const bf16_t* Qp, const bf16_t* Kp, const bf16_t* Vtp, int qb, bf16_t* Op, const float* lq1, const float* lk1, const float* lq2, const float* lk2, const float* subg, float outscale, int tid) {
;     ...
;     const int q15 = qi & 15;
;     const int kx0 = qi * 256 + (((c * 8 + hh) ^ q15) << 4);
;     const int vx = qi * 128 + ((hh ^ ((qi >> 1) & 7)) << 4);
;     ...
;     DA_DMA(0, 0); DA_DMA(1, 1); if (nk > 2) DA_DMA(2, 2);
;     asm volatile("s_waitcnt vmcnt(0)" ::: "memory"); __builtin_amdgcn_s_barrier();
;     f32x16 sa[2], sb[2]; f32x16 negm; float mra = 0.f, mrb = 0.f;
; #pragma unroll
;     for (int i = 0; i < 16; ++i) negm[i] = 0.f;
;     DA_QK(sa, mra, 0);
.LBB0_213:
	v_and_b32_e32 v0, 15, v67
	s_lshl_b32 s19, s9, 3
	v_lshlrev_b32_e32 v2, 8, v15
	v_bitop3_b32 v0, s19, v0, v228 bitop3:0x36
	v_lshl_add_u32 v230, v0, 4, v2
	v_lshrrev_b32_e32 v0, 1, v67
	s_waitcnt vmcnt(0)
	v_bitop3_b32 v0, v228, v0, 7 bitop3:0x78
	v_lshlrev_b32_e32 v2, 7, v15
	s_lshl_b32 s11, s2, 1
	v_lshl_or_b32 v227, v0, 4, v2
	s_barrier
	v_add_u32_e32 v0, 0, v230
	v_xor_b32_e32 v231, 32, v230
	ds_read_b128 v[2:5], v0
	ds_read_b128 v[16:19], v0 offset:8192
	v_add_u32_e32 v0, 0, v231
	ds_read_b128 v[20:23], v0
	ds_read_b128 v[24:27], v0 offset:8192
	s_waitcnt vmcnt(0) lgkmcnt(0)
	v_mfma_f32_32x32x16_bf16 v[98:113], v[2:5], v[190:193], 0
	v_xor_b32_e32 v229, 64, v230
	v_add_u32_e32 v0, 0, v229
	v_xor_b32_e32 v233, 0x60, v230
	ds_read_b128 v[2:5], v0
	ds_read_b128 v[28:31], v0 offset:8192
	v_add_u32_e32 v0, 0, v233
	ds_read_b128 v[32:35], v0
	ds_read_b128 v[36:39], v0 offset:8192
	v_mfma_f32_32x32x16_bf16 v[82:97], v[16:19], v[190:193], 0
	v_mfma_f32_32x32x16_bf16 v[98:113], v[20:23], v[186:189], v[98:113]
	v_mfma_f32_32x32x16_bf16 v[82:97], v[24:27], v[186:189], v[82:97]
	s_waitcnt lgkmcnt(3)
	v_mfma_f32_32x32x16_bf16 v[98:113], v[2:5], v[182:185], v[98:113]
	s_waitcnt lgkmcnt(2)
	v_mfma_f32_32x32x16_bf16 v[82:97], v[28:31], v[182:185], v[82:97]
	s_waitcnt lgkmcnt(1)
	v_mfma_f32_32x32x16_bf16 v[98:113], v[32:35], v[178:181], v[98:113]
	s_waitcnt lgkmcnt(0)
	v_mfma_f32_32x32x16_bf16 v[82:97], v[36:39], v[178:181], v[82:97]
	s_andn2_b64 vcc, exec, s[6:7]
	v_xor_b32_e32 v219, 32, v227
	v_xor_b32_e32 v218, 64, v227
	v_xor_b32_e32 v217, 0x60, v227
	s_cbranch_vccnz .LBB0_227
	s_add_i32 s6, 0, 0x10000
	v_add_u32_e32 v0, v11, v10
	v_add_u32_e32 v234, s6, v227
	v_add_u32_e32 v235, s6, v219
	v_add_u32_e32 v236, s6, v218
	v_add_u32_e32 v237, s6, v217
	v_lshl_add_u64 v[80:81], s[4:5], 0, v[0:1]
	v_add_u32_e32 v0, v14, v10
	s_movk_i32 s6, 0x1800
	v_lshl_add_u64 v[202:203], s[4:5], 0, v[0:1]
	s_add_u32 s4, s18, s0
	v_mul_lo_u32 v0, v12, s6
	v_and_b32_e32 v2, 15, v13
	s_addc_u32 s5, s17, s1
	v_lshl_or_b32 v0, v2, 4, v0
	v_lshl_add_u64 v[204:205], s[4:5], 0, v[0:1]
	v_mul_lo_u32 v0, v8, s6
	v_and_b32_e32 v2, 15, v9
	v_lshl_or_b32 v0, v2, 4, v0
	v_mov_b32_e32 v14, v1
	v_mov_b32_e32 v15, v1
	v_lshl_add_u64 v[206:207], s[4:5], 0, v[0:1]
	v_mov_b32_e32 v0, v1
	v_mov_b32_e32 v2, v1
	v_mov_b32_e32 v3, v1
	v_mov_b32_e32 v4, v1
	v_mov_b32_e32 v5, v1
	v_mov_b32_e32 v6, v1
	v_mov_b32_e32 v7, v1
	v_mov_b32_e32 v8, v1
	v_mov_b32_e32 v9, v1
	v_mov_b32_e32 v10, v1
	v_mov_b32_e32 v11, v1
	v_mov_b32_e32 v12, v1
	v_mov_b32_e32 v13, v1
	v_mov_b64_e32 v[64:65], v[14:15]
	v_mov_b64_e32 v[48:49], v[14:15]
	v_mov_b64_e32 v[32:33], v[14:15]
	v_mov_b32_e32 v232, 0
	v_mov_b64_e32 v[62:63], v[12:13]
	v_mov_b64_e32 v[60:61], v[10:11]
	v_mov_b64_e32 v[58:59], v[8:9]
	v_mov_b64_e32 v[56:57], v[6:7]
	v_mov_b64_e32 v[54:55], v[4:5]
	v_mov_b64_e32 v[52:53], v[2:3]
	v_mov_b64_e32 v[50:51], v[0:1]
	v_mov_b64_e32 v[46:47], v[12:13]
	v_mov_b64_e32 v[44:45], v[10:11]
	v_mov_b64_e32 v[42:43], v[8:9]
	v_mov_b64_e32 v[40:41], v[6:7]
	v_mov_b64_e32 v[38:39], v[4:5]
	v_mov_b64_e32 v[36:37], v[2:3]
	v_mov_b64_e32 v[34:35], v[0:1]
	v_mov_b64_e32 v[30:31], v[12:13]
	v_mov_b64_e32 v[28:29], v[10:11]
	v_mov_b64_e32 v[26:27], v[8:9]
	v_mov_b64_e32 v[24:25], v[6:7]
	v_mov_b64_e32 v[22:23], v[4:5]
	v_mov_b64_e32 v[20:21], v[2:3]
	v_mov_b64_e32 v[18:19], v[0:1]
	v_mov_b64_e32 v[16:17], v[14:15]
	v_readlane_b32 s78, v255, 1
	v_readlane_b32 s20, v255, 4
	v_mov_b32_e32 v224, 0x260
	s_mov_b32 s4, 0
	v_mov_b32_e32 v201, 0xff800000
	v_bfrev_b32_e32 v200, 1
	s_mov_b32 s5, 0x8000
	v_mov_b64_e32 v[14:15], v[12:13]
	v_mov_b64_e32 v[12:13], v[10:11]
	v_mov_b64_e32 v[10:11], v[8:9]
	v_mov_b64_e32 v[8:9], v[6:7]
	v_mov_b64_e32 v[6:7], v[4:5]
	v_mov_b64_e32 v[4:5], v[2:3]
	v_mov_b64_e32 v[2:3], v[0:1]
	v_mov_b32_e32 v114, 0
	v_mov_b32_e32 v115, v232
	v_mov_b32_e32 v116, v232
	v_mov_b32_e32 v117, v232
	v_mov_b32_e32 v118, v232
	v_mov_b32_e32 v119, v232
	v_mov_b32_e32 v120, v232
	v_mov_b32_e32 v121, v232
	v_mov_b32_e32 v122, v232
	v_mov_b32_e32 v123, v232
	v_mov_b32_e32 v124, v232
	v_mov_b32_e32 v125, v232
	v_mov_b32_e32 v126, v232
	v_mov_b32_e32 v127, v232
	v_mov_b32_e32 v128, v232
	v_mov_b32_e32 v129, v232
	v_readlane_b32 s79, v255, 2
	v_readlane_b32 s21, v255, 5
	s_mov_b64 s[18:19], 0xc0000
	s_mov_b64 s[22:23], 0x14580c00
	v_mov_b32_e32 v208, v230
	v_mov_b32_e32 v209, v231
	v_mov_b32_e32 v210, v229
	v_mov_b32_e32 v211, v233
.LBB0_215:
	s_add_i32 s6, s5, 0x4000
	s_and_b32 s6, s6, 0xc000
	s_add_i32 s7, s15, s6
	s_add_i32 s6, s16, s6
	s_mov_b32 s98, s7
	s_mov_b32 s99, s6
	s_waitcnt vmcnt(4)
	s_barrier
	s_add_u32 s100, s74, s36
	s_addc_u32 s101, s75, s37
	s_add_u32 s34, s74, s58
	s_addc_u32 s35, s75, s59
	s_add_i32 s6, s5, 0xffff8000
	s_and_b32 s6, s6, 0x8000
	s_add_i32 s7, s6, 0
	ds_read_b128 v[68:71], v208 offset:16384
	ds_read_b128 v[72:75], v208 offset:24576
	ds_read_b128 v[76:79], v209 offset:16384
	ds_read_b128 v[162:165], v209 offset:24576
	v_max3_f32 v240, v98, v82, v99
	v_max3_f32 v66, v83, v100, v84
	s_waitcnt lgkmcnt(0)
	v_mfma_f32_32x32x16_bf16 v[146:161], v[68:71], v[190:193], v[114:129]
	v_max3_f32 v240, v240, v101, v85
	v_max3_f32 v66, v66, v102, v86
	v_mfma_f32_32x32x16_bf16 v[130:145], v[72:75], v[190:193], v[114:129]
	s_mov_b32 m0, s98
	s_nop 0
	global_load_lds_dwordx4 v206, s[100:101]
	ds_read_b128 v[68:71], v210 offset:16384
	ds_read_b128 v[72:75], v210 offset:24576
	v_max3_f32 v240, v240, v103, v87
	v_max3_f32 v66, v66, v104, v88
	v_mfma_f32_32x32x16_bf16 v[146:161], v[76:79], v[186:189], v[146:161]
	ds_read_b128 v[76:79], v211 offset:16384
	ds_read_b128 v[166:169], v211 offset:24576
	v_max3_f32 v240, v240, v105, v89
	v_max3_f32 v66, v66, v106, v90
	v_mfma_f32_32x32x16_bf16 v[130:145], v[162:165], v[186:189], v[130:145]
	s_waitcnt lgkmcnt(0)
	v_max3_f32 v240, v240, v107, v91
	v_max3_f32 v66, v66, v108, v92
	v_mfma_f32_32x32x16_bf16 v[146:161], v[68:71], v[182:185], v[146:161]
	v_max3_f32 v240, v240, v109, v93
	v_max3_f32 v66, v66, v110, v94
	v_mfma_f32_32x32x16_bf16 v[130:145], v[72:75], v[182:185], v[130:145]
	s_mov_b32 m0, s99
	s_nop 0
	global_load_lds_dwordx4 v80, s[34:35]
	v_max3_f32 v240, v240, v111, v95
	v_max3_f32 v66, v66, v112, v96
	v_mfma_f32_32x32x16_bf16 v[146:161], v[76:79], v[178:181], v[146:161]
	v_max3_f32 v240, v240, v113, v97
	v_max3_f32 v240, v240, v66, v66
	v_mfma_f32_32x32x16_bf16 v[130:145], v[166:169], v[178:181], v[130:145]
	s_add_i32 s7, s7, 0x10000
	v_add_u32_e32 v212, s7, v227
	ds_read_b128 v[194:197], v212
	ds_read_b128 v[76:79], v212 offset:4096
	ds_read_b128 v[72:75], v212 offset:8192
	ds_read_b128 v[68:71], v212 offset:12288
	v_mov_b32_e32 v66, v240
	s_nop 1
	v_permlane32_swap_b32_e32 v240, v66
	v_max3_f32 v198, v240, v66, v66
	s_nop 0
	v_pk_add_f32 v[162:163], v[200:201], v[198:199]
	s_nop 0
	v_cmp_gt_f32_e32 vcc, v162, v163
	s_nop 1
	v_cndmask_b32_e32 v0, v201, v162, vcc
	v_cmp_gt_f32_e32 vcc, v0, v201
	s_cbranch_vccz .LBB0_226
	v_sub_f32_e32 v66, v201, v0
	v_exp_f32_e32 v66, v66
	v_xor_b32_e32 v162, 0x80000000, v0
	v_mov_b32_e32 v163, v162
	v_mov_b32_e32 v164, v162
	v_pk_mul_f32 v[64:65], v[64:65], v[66:67] op_sel_hi:[1,0]
	v_pk_mul_f32 v[62:63], v[62:63], v[66:67] op_sel_hi:[1,0]
	v_pk_mul_f32 v[60:61], v[60:61], v[66:67] op_sel_hi:[1,0]
	v_pk_mul_f32 v[58:59], v[58:59], v[66:67] op_sel_hi:[1,0]
	v_pk_mul_f32 v[56:57], v[56:57], v[66:67] op_sel_hi:[1,0]
	v_pk_mul_f32 v[54:55], v[54:55], v[66:67] op_sel_hi:[1,0]
	v_pk_mul_f32 v[52:53], v[52:53], v[66:67] op_sel_hi:[1,0]
	v_pk_mul_f32 v[50:51], v[50:51], v[66:67] op_sel_hi:[1,0]
	v_pk_mul_f32 v[48:49], v[48:49], v[66:67] op_sel_hi:[1,0]
	v_pk_mul_f32 v[46:47], v[46:47], v[66:67] op_sel_hi:[1,0]
	v_pk_mul_f32 v[44:45], v[44:45], v[66:67] op_sel_hi:[1,0]
	v_pk_mul_f32 v[42:43], v[42:43], v[66:67] op_sel_hi:[1,0]
	v_pk_mul_f32 v[40:41], v[40:41], v[66:67] op_sel_hi:[1,0]
	v_pk_mul_f32 v[38:39], v[38:39], v[66:67] op_sel_hi:[1,0]
	v_pk_mul_f32 v[36:37], v[36:37], v[66:67] op_sel_hi:[1,0]
	v_pk_mul_f32 v[34:35], v[34:35], v[66:67] op_sel_hi:[1,0]
	v_pk_mul_f32 v[32:33], v[32:33], v[66:67] op_sel_hi:[1,0]
	v_pk_mul_f32 v[30:31], v[30:31], v[66:67] op_sel_hi:[1,0]
	v_pk_mul_f32 v[28:29], v[28:29], v[66:67] op_sel_hi:[1,0]
	v_pk_mul_f32 v[26:27], v[26:27], v[66:67] op_sel_hi:[1,0]
	v_pk_mul_f32 v[24:25], v[24:25], v[66:67] op_sel_hi:[1,0]
	v_pk_mul_f32 v[22:23], v[22:23], v[66:67] op_sel_hi:[1,0]
	v_pk_mul_f32 v[20:21], v[20:21], v[66:67] op_sel_hi:[1,0]
	v_pk_mul_f32 v[18:19], v[18:19], v[66:67] op_sel_hi:[1,0]
	v_pk_mul_f32 v[16:17], v[16:17], v[66:67] op_sel_hi:[1,0]
	v_pk_mul_f32 v[14:15], v[14:15], v[66:67] op_sel_hi:[1,0]
	v_pk_mul_f32 v[12:13], v[12:13], v[66:67] op_sel_hi:[1,0]
	v_pk_mul_f32 v[10:11], v[10:11], v[66:67] op_sel_hi:[1,0]
	v_pk_mul_f32 v[8:9], v[8:9], v[66:67] op_sel_hi:[1,0]
	v_pk_mul_f32 v[6:7], v[6:7], v[66:67] op_sel_hi:[1,0]
	v_pk_mul_f32 v[4:5], v[4:5], v[66:67] op_sel_hi:[1,0]
	v_pk_mul_f32 v[2:3], v[2:3], v[66:67] op_sel_hi:[1,0]
	v_mul_f32_e32 v232, v232, v66
	v_mov_b32_e32 v165, v162
	v_mov_b32_e32 v166, v162
	v_mov_b32_e32 v167, v162
	v_mov_b32_e32 v168, v162
	v_mov_b32_e32 v169, v162
	v_mov_b32_e32 v170, v162
	v_mov_b32_e32 v171, v162
	v_mov_b32_e32 v172, v162
	v_mov_b32_e32 v173, v162
	v_mov_b32_e32 v174, v162
	v_mov_b32_e32 v175, v162
	v_mov_b32_e32 v176, v162
	v_mov_b32_e32 v177, v162
	v_mov_b32_e32 v201, v0
	v_mov_b32_e32 v66, v162
	v_mov_b32_e32 v115, v162
	v_mov_b32_e32 v116, v162
	v_mov_b32_e32 v117, v162
	v_mov_b32_e32 v118, v162
	v_mov_b32_e32 v119, v162
	v_mov_b32_e32 v120, v162
	v_mov_b32_e32 v121, v162
	v_mov_b32_e32 v122, v162
	v_mov_b32_e32 v123, v162
	v_mov_b32_e32 v124, v162
	v_mov_b32_e32 v125, v162
	v_mov_b32_e32 v126, v162
	v_mov_b32_e32 v127, v162
	v_mov_b32_e32 v128, v162
	v_mov_b32_e32 v129, v162
	v_sub_f32_e32 v0, v0, v200
	v_cmp_neq_f32_e32 vcc, 0, v0
	s_cbranch_vccz .LBB0_218

; #define DA_WAIT_BAR(N) do { asm volatile("s_waitcnt vmcnt(" #N ")" ::: "memory"); __builtin_amdgcn_s_barrier(); } while (0)
; __device__ __forceinline__ void dattn_unit(LAS unsigned char* lds, const bf16_t* Qp, const bf16_t* Kp, const bf16_t* Vtp, int qb, bf16_t* Op, const float* lq1, const float* lk1, const float* lq2, const float* lk2, const float* subg, float outscale, int tid) {
;     ...
;     DA_DMA(0, 0); DA_DMA(1, 1); if (nk > 2) DA_DMA(2, 2);
;     asm volatile("s_waitcnt vmcnt(0)" ::: "memory"); __builtin_amdgcn_s_barrier();
;     f32x16 sa[2], sb[2]; f32x16 negm; float mra = 0.f, mrb = 0.f;
; #pragma unroll
;     for (int i = 0; i < 16; ++i) negm[i] = 0.f;
;     DA_QK(sa, mra, 0);
;     for (int kt = 0; kt < nfull; kt += 2) {
;         DA_WAIT_BAR(4); DA_DMA(kt + 3, (kt + 3) & 3); DA_QK(sb, mrb, (kt + 1) & 3); DA_SOFTMAX_PV(sa, mra, kt & 3, false, kt);
;         DA_WAIT_BAR(4); if (kt + 4 < nk) DA_DMA(kt + 4, kt & 3); DA_QK(sa, mra, (kt + 2) & 3); DA_SOFTMAX_PV(sb, mrb, (kt + 1) & 3, false, kt + 1);
.LBB0_218:
	v_exp_f32_e32 v198, v98
	v_exp_f32_e32 v0, v99
	v_exp_f32_e32 v200, v100
	v_exp_f32_e32 v98, v101
	v_exp_f32_e32 v238, v102
	v_exp_f32_e32 v99, v103
	v_exp_f32_e32 v239, v104
	v_exp_f32_e32 v100, v105
	v_cvt_pk_bf16_f32 v240, v198, v0
	v_cvt_pk_bf16_f32 v241, v200, v98
	v_cvt_pk_bf16_f32 v242, v238, v99
	v_cvt_pk_bf16_f32 v243, v239, v100
	v_exp_f32_e32 v105, v106
	s_waitcnt lgkmcnt(0)
	v_mfma_f32_32x32x16_bf16 v[50:65], v[194:197], v[240:243], v[50:65]
	v_add_u32_e32 v213, s7, v219
	v_exp_f32_e32 v101, v107
	v_exp_f32_e32 v106, v108
	v_exp_f32_e32 v102, v109
	v_mfma_f32_32x32x16_bf16 v[34:49], v[76:79], v[240:243], v[34:49]
	s_add_i32 m0, s98, 0x2000
	s_nop 0
	global_load_lds_dwordx4 v204, s[100:101]
	v_exp_f32_e32 v107, v110
	v_exp_f32_e32 v103, v111
	v_exp_f32_e32 v108, v112
	v_mfma_f32_32x32x16_bf16 v[18:33], v[72:75], v[240:243], v[18:33]
	ds_read_b128 v[72:75], v213
	ds_read_b128 v[76:79], v213 offset:4096
	ds_read_b128 v[194:197], v213 offset:8192
	ds_read_b128 v[220:223], v213 offset:12288
	v_exp_f32_e32 v104, v113
	v_cvt_pk_bf16_f32 v244, v105, v101
	v_cvt_pk_bf16_f32 v245, v106, v102
	v_mfma_f32_32x32x16_bf16 v[2:17], v[68:71], v[240:243], v[2:17]
	v_cvt_pk_bf16_f32 v246, v107, v103
	v_cvt_pk_bf16_f32 v247, v108, v104
	v_exp_f32_e32 v109, v82
	v_exp_f32_e32 v82, v83
	s_waitcnt lgkmcnt(0)
	v_mfma_f32_32x32x16_bf16 v[50:65], v[72:75], v[244:247], v[50:65]
	v_add_u32_e32 v214, s7, v218
	v_exp_f32_e32 v110, v84
	v_exp_f32_e32 v83, v85
	v_exp_f32_e32 v111, v86
	v_mfma_f32_32x32x16_bf16 v[34:49], v[76:79], v[244:247], v[34:49]
	s_add_i32 m0, s99, 0x2000
	s_nop 0
	global_load_lds_dwordx4 v202, s[34:35]
	v_exp_f32_e32 v84, v87
	v_exp_f32_e32 v112, v88
	v_exp_f32_e32 v85, v89
	v_mfma_f32_32x32x16_bf16 v[18:33], v[194:197], v[244:247], v[18:33]
	ds_read_b128 v[68:71], v214
	ds_read_b128 v[72:75], v214 offset:4096
	ds_read_b128 v[76:79], v214 offset:8192
	ds_read_b128 v[194:197], v214 offset:12288
	v_exp_f32_e32 v90, v90
	v_exp_f32_e32 v86, v91
	v_exp_f32_e32 v91, v92
	v_mfma_f32_32x32x16_bf16 v[2:17], v[220:223], v[244:247], v[2:17]
	v_exp_f32_e32 v87, v93
	v_exp_f32_e32 v92, v94
	v_exp_f32_e32 v88, v95
	v_exp_f32_e32 v93, v96
	v_exp_f32_e32 v89, v97
	v_cvt_pk_bf16_f32 v94, v109, v82
	v_cvt_pk_bf16_f32 v95, v110, v83
	v_cvt_pk_bf16_f32 v96, v111, v84
	v_cvt_pk_bf16_f32 v97, v112, v85
	v_add_f32_e32 v240, 0, v198
	v_add_f32_e32 v241, 0, v0
	s_waitcnt lgkmcnt(0)
	v_mfma_f32_32x32x16_bf16 v[50:65], v[68:71], v[94:97], v[50:65]
	v_add_u32_e32 v215, s7, v217
	v_cvt_pk_bf16_f32 v248, v90, v86
	v_cvt_pk_bf16_f32 v249, v91, v87
	v_add_f32_e32 v240, v200, v240
	v_add_f32_e32 v241, v98, v241
	v_add_f32_e32 v240, v238, v240
	v_mfma_f32_32x32x16_bf16 v[34:49], v[72:75], v[94:97], v[34:49]
	v_cvt_pk_bf16_f32 v250, v92, v88
	v_cvt_pk_bf16_f32 v251, v93, v89
	v_add_f32_e32 v241, v99, v241
	v_add_f32_e32 v240, v239, v240
	v_add_f32_e32 v241, v100, v241
	v_mfma_f32_32x32x16_bf16 v[18:33], v[76:79], v[94:97], v[18:33]
	ds_read_b128 v[68:71], v215
	ds_read_b128 v[72:75], v215 offset:4096
	ds_read_b128 v[76:79], v215 offset:8192
	ds_read_b128 v[220:223], v215 offset:12288
	v_add_f32_e32 v240, v105, v240
	v_add_f32_e32 v241, v101, v241
	v_add_f32_e32 v240, v106, v240
	v_add_f32_e32 v241, v102, v241
	v_mfma_f32_32x32x16_bf16 v[2:17], v[194:197], v[94:97], v[2:17]
	v_add_f32_e32 v240, v107, v240
	v_add_f32_e32 v241, v103, v241
	v_add_f32_e32 v240, v108, v240
	v_add_f32_e32 v241, v104, v241
	v_add_f32_e32 v240, v109, v240
	v_add_f32_e32 v241, v82, v241
	s_waitcnt lgkmcnt(0)
	v_mfma_f32_32x32x16_bf16 v[50:65], v[68:71], v[248:251], v[50:65]
	v_add_f32_e32 v240, v110, v240
	v_add_f32_e32 v241, v83, v241
	v_add_f32_e32 v240, v111, v240
	v_add_f32_e32 v241, v84, v241
	v_add_f32_e32 v240, v112, v240
	v_add_f32_e32 v241, v85, v241
	v_mfma_f32_32x32x16_bf16 v[34:49], v[72:75], v[248:251], v[34:49]
	v_add_f32_e32 v240, v90, v240
	v_add_f32_e32 v241, v86, v241
	v_add_f32_e32 v240, v91, v240
	v_add_f32_e32 v241, v87, v241
	v_add_f32_e32 v240, v92, v240
	v_add_f32_e32 v241, v88, v241
	v_mfma_f32_32x32x16_bf16 v[18:33], v[76:79], v[248:251], v[18:33]
	v_add_f32_e32 v240, v93, v240
	v_add_f32_e32 v241, v89, v241
	v_add_f32_e32 v0, v241, v240
	v_add_f32_e32 v0, v232, v0
	v_mfma_f32_32x32x16_bf16 v[2:17], v[220:223], v[248:251], v[2:17]
	s_waitcnt vmcnt(4)
	s_add_i32 s17, s4, 4
	s_cmp_gt_u32 s17, s11
	s_barrier
	s_cbranch_scc1 .LBB0_220
	s_add_i32 s17, s15, s6
	s_add_i32 s7, s7, s14
	s_add_u32 s100, s74, s22
	s_addc_u32 s101, s75, s23
	s_add_u32 s34, s74, 0x20400200
	s_addc_u32 s35, s75, 0
	s_mov_b32 m0, s17
	s_nop 0
	global_load_lds_dwordx4 v206, s[100:101]
	s_mov_b32 m0, s7
	s_nop 0
	global_load_lds_dwordx4 v80, s[34:35]
	s_add_i32 m0, s17, 0x2000
	s_nop 0
	global_load_lds_dwordx4 v204, s[100:101]
	s_add_i32 m0, s7, 0x2000
	s_nop 0
	global_load_lds_dwordx4 v202, s[34:35]
.LBB0_220:
	s_bitset1_b32 s6, 14
	s_and_b32 s7, s5, 0x8000
	s_add_i32 s7, s7, 0
	v_xor_b32_e32 v208, 0x8000, v208
	v_xor_b32_e32 v209, 0x8000, v209
	ds_read_b128 v[68:71], v208
	ds_read_b128 v[72:75], v208 offset:8192
	ds_read_b128 v[76:79], v209
	ds_read_b128 v[194:197], v209 offset:8192
	s_waitcnt lgkmcnt(0)
	v_mfma_f32_32x32x16_bf16 v[98:113], v[68:71], v[190:193], v[162:177]
	v_mfma_f32_32x32x16_bf16 v[82:97], v[72:75], v[190:193], v[162:177]
	v_xor_b32_e32 v210, 0x8000, v210
	ds_read_b128 v[68:71], v210
	ds_read_b128 v[72:75], v210 offset:8192
	s_nop 3
	v_xor_b32_e32 v211, 0x8000, v211
	v_mfma_f32_32x32x16_bf16 v[98:113], v[76:79], v[186:189], v[98:113]
	ds_read_b128 v[76:79], v211
	ds_read_b128 v[164:167], v211 offset:8192
	v_max3_f32 v163, v146, v130, v147
	v_max3_f32 v168, v131, v148, v132
	v_mfma_f32_32x32x16_bf16 v[82:97], v[194:197], v[186:189], v[82:97]
	s_waitcnt lgkmcnt(0)
	v_max3_f32 v163, v163, v149, v133
	v_max3_f32 v168, v168, v150, v134
	v_mfma_f32_32x32x16_bf16 v[98:113], v[68:71], v[182:185], v[98:113]
	v_max3_f32 v163, v163, v151, v135
	v_max3_f32 v168, v168, v152, v136
	v_mfma_f32_32x32x16_bf16 v[82:97], v[72:75], v[182:185], v[82:97]
	v_max3_f32 v163, v163, v153, v137
	v_max3_f32 v168, v168, v154, v138
	v_max3_f32 v163, v163, v155, v139
	v_max3_f32 v168, v168, v156, v140
	v_mfma_f32_32x32x16_bf16 v[98:113], v[76:79], v[178:181], v[98:113]
	v_max3_f32 v163, v163, v157, v141
	v_max3_f32 v168, v168, v158, v142
	v_max3_f32 v163, v163, v159, v143
	v_max3_f32 v168, v168, v160, v144
	v_mfma_f32_32x32x16_bf16 v[82:97], v[164:167], v[178:181], v[82:97]
	ds_read_b128 v[164:167], v212 offset:16384
	ds_read_b128 v[76:79], v212 offset:20480
	ds_read_b128 v[72:75], v212 offset:24576
	ds_read_b128 v[68:71], v212 offset:28672
	v_max3_f32 v163, v163, v161, v145
	v_max3_f32 v163, v163, v168, v168
	v_mov_b32_e32 v168, v163
	s_nop 1
	v_permlane32_swap_b32_e32 v163, v168
	v_max3_f32 v163, v163, v168, v168
	v_add_f32_e32 v168, 0x41000000, v201
	v_sub_f32_e32 v163, v163, v114
	v_cmp_gt_f32_e32 vcc, v163, v168
	s_nop 1
	v_cndmask_b32_e32 v163, v201, v163, vcc
	v_cmp_gt_f32_e32 vcc, v163, v201
	s_cbranch_vccz .LBB0_222
	v_sub_f32_e32 v66, v201, v163
	v_exp_f32_e32 v116, v66
	v_xor_b32_e32 v66, 0x80000000, v163
	v_mov_b32_e32 v201, v163
	v_mov_b32_e32 v115, v66
	v_pk_mul_f32 v[64:65], v[64:65], v[116:117] op_sel_hi:[1,0]
	v_pk_mul_f32 v[62:63], v[62:63], v[116:117] op_sel_hi:[1,0]
	v_pk_mul_f32 v[60:61], v[60:61], v[116:117] op_sel_hi:[1,0]
	v_pk_mul_f32 v[58:59], v[58:59], v[116:117] op_sel_hi:[1,0]
	v_pk_mul_f32 v[56:57], v[56:57], v[116:117] op_sel_hi:[1,0]
	v_pk_mul_f32 v[54:55], v[54:55], v[116:117] op_sel_hi:[1,0]
	v_pk_mul_f32 v[52:53], v[52:53], v[116:117] op_sel_hi:[1,0]
	v_pk_mul_f32 v[50:51], v[50:51], v[116:117] op_sel_hi:[1,0]
	v_pk_mul_f32 v[48:49], v[48:49], v[116:117] op_sel_hi:[1,0]
	v_pk_mul_f32 v[46:47], v[46:47], v[116:117] op_sel_hi:[1,0]
	v_pk_mul_f32 v[44:45], v[44:45], v[116:117] op_sel_hi:[1,0]
	v_pk_mul_f32 v[42:43], v[42:43], v[116:117] op_sel_hi:[1,0]
	v_pk_mul_f32 v[40:41], v[40:41], v[116:117] op_sel_hi:[1,0]
	v_pk_mul_f32 v[38:39], v[38:39], v[116:117] op_sel_hi:[1,0]
	v_pk_mul_f32 v[36:37], v[36:37], v[116:117] op_sel_hi:[1,0]
	v_pk_mul_f32 v[34:35], v[34:35], v[116:117] op_sel_hi:[1,0]
	v_pk_mul_f32 v[32:33], v[32:33], v[116:117] op_sel_hi:[1,0]
	v_pk_mul_f32 v[30:31], v[30:31], v[116:117] op_sel_hi:[1,0]
	v_pk_mul_f32 v[28:29], v[28:29], v[116:117] op_sel_hi:[1,0]
	v_pk_mul_f32 v[26:27], v[26:27], v[116:117] op_sel_hi:[1,0]
	v_pk_mul_f32 v[24:25], v[24:25], v[116:117] op_sel_hi:[1,0]
	v_pk_mul_f32 v[22:23], v[22:23], v[116:117] op_sel_hi:[1,0]
	v_pk_mul_f32 v[20:21], v[20:21], v[116:117] op_sel_hi:[1,0]
	v_pk_mul_f32 v[18:19], v[18:19], v[116:117] op_sel_hi:[1,0]
	v_pk_mul_f32 v[16:17], v[16:17], v[116:117] op_sel_hi:[1,0]
	v_pk_mul_f32 v[14:15], v[14:15], v[116:117] op_sel_hi:[1,0]
	v_pk_mul_f32 v[12:13], v[12:13], v[116:117] op_sel_hi:[1,0]
	v_pk_mul_f32 v[10:11], v[10:11], v[116:117] op_sel_hi:[1,0]
	v_pk_mul_f32 v[8:9], v[8:9], v[116:117] op_sel_hi:[1,0]
	v_pk_mul_f32 v[6:7], v[6:7], v[116:117] op_sel_hi:[1,0]
	v_pk_mul_f32 v[4:5], v[4:5], v[116:117] op_sel_hi:[1,0]
	v_pk_mul_f32 v[2:3], v[2:3], v[116:117] op_sel_hi:[1,0]
	v_mul_f32_e32 v0, v0, v116
	v_mov_b32_e32 v116, v66
	v_mov_b32_e32 v117, v66
	v_mov_b32_e32 v118, v66
	v_mov_b32_e32 v119, v66
	v_mov_b32_e32 v120, v66
	v_mov_b32_e32 v121, v66
	v_mov_b32_e32 v122, v66
	v_mov_b32_e32 v123, v66
	v_mov_b32_e32 v124, v66
	v_mov_b32_e32 v125, v66
	v_mov_b32_e32 v126, v66
	v_mov_b32_e32 v127, v66
	v_mov_b32_e32 v128, v66
	v_mov_b32_e32 v129, v66

; #define DA_WAIT_BAR(N) do { asm volatile("s_waitcnt vmcnt(" #N ")" ::: "memory"); __builtin_amdgcn_s_barrier(); } while (0)
; __device__ __forceinline__ void dattn_unit(LAS unsigned char* lds, const bf16_t* Qp, const bf16_t* Kp, const bf16_t* Vtp, int qb, bf16_t* Op, const float* lq1, const float* lk1, const float* lq2, const float* lk2, const float* subg, float outscale, int tid) {
;     ...
;     DA_DMA(0, 0); DA_DMA(1, 1); if (nk > 2) DA_DMA(2, 2);
;     asm volatile("s_waitcnt vmcnt(0)" ::: "memory"); __builtin_amdgcn_s_barrier();
;     f32x16 sa[2], sb[2]; f32x16 negm; float mra = 0.f, mrb = 0.f;
; #pragma unroll
;     for (int i = 0; i < 16; ++i) negm[i] = 0.f;
;     DA_QK(sa, mra, 0);
;     for (int kt = 0; kt < nfull; kt += 2) {
;         DA_WAIT_BAR(4); DA_DMA(kt + 3, (kt + 3) & 3); DA_QK(sb, mrb, (kt + 1) & 3); DA_SOFTMAX_PV(sa, mra, kt & 3, false, kt);
;         DA_WAIT_BAR(4); if (kt + 4 < nk) DA_DMA(kt + 4, kt & 3); DA_QK(sa, mra, (kt + 2) & 3); DA_SOFTMAX_PV(sb, mrb, (kt + 1) & 3, false, kt + 1);
;     }
.LBB0_224:
	v_exp_f32_e32 v168, v146
	v_exp_f32_e32 v169, v147
	v_exp_f32_e32 v170, v148
	v_exp_f32_e32 v171, v149
	v_exp_f32_e32 v172, v150
	v_exp_f32_e32 v173, v151
	v_exp_f32_e32 v174, v152
	v_exp_f32_e32 v175, v153
	v_cvt_pk_bf16_f32 v146, v168, v169
	v_cvt_pk_bf16_f32 v147, v170, v171
	v_cvt_pk_bf16_f32 v148, v172, v173
	v_cvt_pk_bf16_f32 v149, v174, v175
	v_exp_f32_e32 v154, v154
	s_waitcnt lgkmcnt(0)
	v_mfma_f32_32x32x16_bf16 v[50:65], v[164:167], v[146:149], v[50:65]
	v_exp_f32_e32 v155, v155
	v_pk_add_f32 v[168:169], v[168:169], 0 op_sel_hi:[1,0]
	v_exp_f32_e32 v156, v156
	v_mfma_f32_32x32x16_bf16 v[34:49], v[76:79], v[146:149], v[34:49]
	v_exp_f32_e32 v157, v157
	v_pk_add_f32 v[168:169], v[170:171], v[168:169]
	v_exp_f32_e32 v158, v158
	v_mfma_f32_32x32x16_bf16 v[18:33], v[72:75], v[146:149], v[18:33]
	ds_read_b128 v[72:75], v213 offset:16384
	ds_read_b128 v[76:79], v213 offset:20480
	ds_read_b128 v[240:243], v213 offset:24576
	ds_read_b128 v[244:247], v213 offset:28672
	v_exp_f32_e32 v159, v159
	v_pk_add_f32 v[168:169], v[172:173], v[168:169]
	v_exp_f32_e32 v160, v160
	v_mfma_f32_32x32x16_bf16 v[2:17], v[68:71], v[146:149], v[2:17]
	v_exp_f32_e32 v161, v161
	v_pk_add_f32 v[168:169], v[174:175], v[168:169]
	v_cvt_pk_bf16_f32 v150, v154, v155
	v_cvt_pk_bf16_f32 v151, v156, v157
	v_cvt_pk_bf16_f32 v152, v158, v159
	v_cvt_pk_bf16_f32 v153, v160, v161
	v_exp_f32_e32 v170, v130
	s_waitcnt lgkmcnt(0)
	v_mfma_f32_32x32x16_bf16 v[50:65], v[72:75], v[150:153], v[50:65]
	v_exp_f32_e32 v171, v131
	v_pk_add_f32 v[154:155], v[154:155], v[168:169]
	v_exp_f32_e32 v172, v132
	v_mfma_f32_32x32x16_bf16 v[34:49], v[76:79], v[150:153], v[34:49]
	v_exp_f32_e32 v173, v133
	v_pk_add_f32 v[154:155], v[156:157], v[154:155]
	v_exp_f32_e32 v174, v134
	v_mfma_f32_32x32x16_bf16 v[18:33], v[240:243], v[150:153], v[18:33]
	ds_read_b128 v[68:71], v214 offset:16384
	ds_read_b128 v[72:75], v214 offset:20480
	ds_read_b128 v[76:79], v214 offset:24576
	ds_read_b128 v[240:243], v214 offset:28672
	v_exp_f32_e32 v175, v135
	v_pk_add_f32 v[154:155], v[158:159], v[154:155]
	v_exp_f32_e32 v176, v136
	v_mfma_f32_32x32x16_bf16 v[2:17], v[244:247], v[150:153], v[2:17]
	v_exp_f32_e32 v177, v137
	v_pk_add_f32 v[154:155], v[160:161], v[154:155]
	v_cvt_pk_bf16_f32 v130, v170, v171
	v_cvt_pk_bf16_f32 v131, v172, v173
	v_cvt_pk_bf16_f32 v132, v174, v175
	v_cvt_pk_bf16_f32 v133, v176, v177
	v_exp_f32_e32 v138, v138
	s_waitcnt lgkmcnt(0)
	v_mfma_f32_32x32x16_bf16 v[50:65], v[68:71], v[130:133], v[50:65]
	v_exp_f32_e32 v139, v139
	v_pk_add_f32 v[154:155], v[170:171], v[154:155]
	v_exp_f32_e32 v140, v140
	v_mfma_f32_32x32x16_bf16 v[34:49], v[72:75], v[130:133], v[34:49]
	v_exp_f32_e32 v141, v141
	v_pk_add_f32 v[154:155], v[172:173], v[154:155]
	v_exp_f32_e32 v142, v142
	v_mfma_f32_32x32x16_bf16 v[18:33], v[76:79], v[130:133], v[18:33]
	ds_read_b128 v[68:71], v215 offset:16384
	ds_read_b128 v[72:75], v215 offset:20480
	ds_read_b128 v[76:79], v215 offset:24576
	ds_read_b128 v[244:247], v215 offset:28672
	v_exp_f32_e32 v143, v143
	v_pk_add_f32 v[154:155], v[174:175], v[154:155]
	v_exp_f32_e32 v144, v144
	v_mfma_f32_32x32x16_bf16 v[2:17], v[240:243], v[130:133], v[2:17]
	v_exp_f32_e32 v145, v145
	v_pk_add_f32 v[154:155], v[176:177], v[154:155]
	v_cvt_pk_bf16_f32 v134, v138, v139
	v_pk_add_f32 v[138:139], v[138:139], v[154:155]
	s_add_i32 s4, s4, 2
	v_pk_add_f32 v[138:139], v[140:141], v[138:139]
	v_pk_add_f32 v[138:139], v[142:143], v[138:139]
	v_pk_add_f32 v[138:139], v[144:145], v[138:139]
	v_cvt_pk_bf16_f32 v135, v140, v141
	v_cvt_pk_bf16_f32 v136, v142, v143
	v_cvt_pk_bf16_f32 v137, v144, v145
	v_add_f32_e32 v114, v138, v139
	s_waitcnt lgkmcnt(0)
	v_mfma_f32_32x32x16_bf16 v[50:65], v[68:71], v[134:137], v[50:65]
	v_add_f32_e32 v232, v0, v114
	v_mfma_f32_32x32x16_bf16 v[34:49], v[72:75], v[134:137], v[34:49]
	v_mfma_f32_32x32x16_bf16 v[18:33], v[76:79], v[134:137], v[18:33]
	v_mfma_f32_32x32x16_bf16 v[2:17], v[244:247], v[134:137], v[2:17]
	s_add_i32 s5, s5, 0x8000
	v_xor_b32_e32 v200, 0x80000000, v162
	v_add_u32_e32 v80, s96, v80
	v_add_u32_e32 v202, s96, v202
	v_add_u32_e32 v204, s18, v204
	s_cmp_ge_u32 s4, s11
	v_add_u32_e32 v206, s18, v206
	s_cbranch_scc1 .LBB0_228
	v_mov_b32_e32 v114, v66
	s_branch .LBB0_215
